# attention queues: heavy and light differential-head items interleaved (q-blocks descending) instead of all heavy items first
# speedup vs baseline: 1.0235x; 1.0143x over previous
.LBB0_840:
	s_andn2_b64 vcc, exec, s[38:39]
	s_cbranch_vccnz .LBB0_842
	s_add_i32 s4, s54, -12
	s_lshr_b32 s30, s4, 1
	s_andn2_b32 s50, 0x7f, s30
	s_bitcmp0_b32 s4, 0
	v_readlane_b32 s4, v250, 18
	v_readlane_b32 s5, v250, 19
	s_cselect_b32 s6, 2, 1
	s_cselect_b32 s30, 3, 0
	s_and_b64 s[4:5], s[4:5], exec
	s_cselect_b32 s6, s30, s6
	s_mov_b64 s[4:5], 0
	s_mov_b32 s55, s71
